# P4 GLA chunk scan: 16 loads of 8 chunks in flight with counted waits instead of 32 fully serialized load/store round trips per thread
# speedup vs baseline: 1.0089x; 1.0028x over previous
.LBB0_718:
	v_lshl_add_u64 v[64:65], v[10:11], 0, s[12:13]
	s_mov_b64 s[14:15], 0x8000
	v_lshl_add_u64 v[66:67], v[64:65], 0, s[14:15]
	v_lshl_add_u64 v[68:69], v[66:67], 0, s[14:15]
	v_lshl_add_u64 v[70:71], v[68:69], 0, s[14:15]
	v_lshl_add_u64 v[72:73], v[70:71], 0, s[14:15]
	v_lshl_add_u64 v[74:75], v[72:73], 0, s[14:15]
	v_lshl_add_u64 v[76:77], v[74:75], 0, s[14:15]
	v_lshl_add_u64 v[78:79], v[76:77], 0, s[14:15]
	global_load_dwordx4 v[80:83], v[64:65], off
	global_load_dword v112, v[12:13], off offset:-1792
	global_load_dwordx4 v[84:87], v[66:67], off
	global_load_dword v114, v[12:13], off offset:-1536
	global_load_dwordx4 v[88:91], v[68:69], off
	global_load_dword v116, v[12:13], off offset:-1280
	global_load_dwordx4 v[92:95], v[70:71], off
	global_load_dword v118, v[12:13], off offset:-1024
	global_load_dwordx4 v[96:99], v[72:73], off
	global_load_dword v120, v[12:13], off offset:-768
	global_load_dwordx4 v[100:103], v[74:75], off
	global_load_dword v122, v[12:13], off offset:-512
	global_load_dwordx4 v[104:107], v[76:77], off
	global_load_dword v124, v[12:13], off offset:-256
	global_load_dwordx4 v[108:111], v[78:79], off
	global_load_dword v126, v[12:13], off
	s_waitcnt vmcnt(14)
	global_store_dwordx4 v[64:65], v[2:5], off
	v_pk_fma_f32 v[128:129], v[2:3], v[112:113], v[80:81] op_sel_hi:[1,0,1]
	v_pk_fma_f32 v[130:131], v[4:5], v[112:113], v[82:83] op_sel_hi:[1,0,1]
	s_waitcnt vmcnt(13)
	global_store_dwordx4 v[66:67], v[128:131], off
	v_pk_fma_f32 v[2:3], v[128:129], v[114:115], v[84:85] op_sel_hi:[1,0,1]
	v_pk_fma_f32 v[4:5], v[130:131], v[114:115], v[86:87] op_sel_hi:[1,0,1]
	s_waitcnt vmcnt(12)
	global_store_dwordx4 v[68:69], v[2:5], off
	v_pk_fma_f32 v[128:129], v[2:3], v[116:117], v[88:89] op_sel_hi:[1,0,1]
	v_pk_fma_f32 v[130:131], v[4:5], v[116:117], v[90:91] op_sel_hi:[1,0,1]
	s_waitcnt vmcnt(11)
	global_store_dwordx4 v[70:71], v[128:131], off
	v_pk_fma_f32 v[2:3], v[128:129], v[118:119], v[92:93] op_sel_hi:[1,0,1]
	v_pk_fma_f32 v[4:5], v[130:131], v[118:119], v[94:95] op_sel_hi:[1,0,1]
	s_waitcnt vmcnt(10)
	global_store_dwordx4 v[72:73], v[2:5], off
	v_pk_fma_f32 v[128:129], v[2:3], v[120:121], v[96:97] op_sel_hi:[1,0,1]
	v_pk_fma_f32 v[130:131], v[4:5], v[120:121], v[98:99] op_sel_hi:[1,0,1]
	s_waitcnt vmcnt(9)
	global_store_dwordx4 v[74:75], v[128:131], off
	v_pk_fma_f32 v[2:3], v[128:129], v[122:123], v[100:101] op_sel_hi:[1,0,1]
	v_pk_fma_f32 v[4:5], v[130:131], v[122:123], v[102:103] op_sel_hi:[1,0,1]
	s_waitcnt vmcnt(8)
	global_store_dwordx4 v[76:77], v[2:5], off
	v_pk_fma_f32 v[128:129], v[2:3], v[124:125], v[104:105] op_sel_hi:[1,0,1]
	v_pk_fma_f32 v[130:131], v[4:5], v[124:125], v[106:107] op_sel_hi:[1,0,1]
	s_waitcnt vmcnt(7)
	global_store_dwordx4 v[78:79], v[128:131], off
	v_pk_fma_f32 v[2:3], v[128:129], v[126:127], v[108:109] op_sel_hi:[1,0,1]
	v_pk_fma_f32 v[4:5], v[130:131], v[126:127], v[110:111] op_sel_hi:[1,0,1]
	s_add_u32 s12, s12, 0x40000
	s_addc_u32 s13, s13, 0
	s_mov_b64 s[14:15], 0x800
	v_lshl_add_u64 v[12:13], v[12:13], 0, s[14:15]
	s_cmp_eq_u32 s12, 0x100000
	s_cbranch_scc0 .LBB0_718
	v_readlane_b32 s12, v254, 12
	v_lshlrev_b64 v[8:9], 15, v[8:9]
	v_readlane_b32 s22, v254, 22
	v_readlane_b32 s23, v254, 23
	v_lshlrev_b32_e32 v6, 4, v19
	v_add_u32_e32 v19, s2, v19
	s_mov_b32 s12, 0x1ffff
	v_lshl_add_u64 v[8:9], s[22:23], 0, v[8:9]
	v_and_b32_e32 v6, 0x7ff0, v6
	v_cmp_lt_i32_e32 vcc, s12, v19
	v_lshl_add_u64 v[8:9], v[8:9], 0, v[6:7]
	s_or_b64 s[8:9], vcc, s[8:9]
	v_add_u32_e32 v18, s11, v18
	v_readlane_b32 s13, v254, 13
	v_readlane_b32 s14, v254, 14
	v_readlane_b32 s15, v254, 15
	v_readlane_b32 s16, v254, 16
	v_readlane_b32 s17, v254, 17
	v_readlane_b32 s18, v254, 18
	v_readlane_b32 s19, v254, 19
	v_readlane_b32 s20, v254, 20
	v_readlane_b32 s21, v254, 21
	v_readlane_b32 s24, v254, 24
	v_readlane_b32 s25, v254, 25
	v_readlane_b32 s26, v254, 26
	v_readlane_b32 s27, v254, 27
	global_store_dwordx4 v[8:9], v[2:5], off
	s_andn2_b64 exec, exec, s[8:9]
	s_cbranch_execnz .LBB0_717
